# unpacked v_pk_mul in FFN13 epilogues; s_setprio 1 during attention PV+QK segment
# baseline (speedup 1.0000x reference)
; DI unsigned cvtpk(float lo, float hi) { f32x2_t v = {lo, hi}; bf16x2_t b = __builtin_convertvector(v, bf16x2_t); return __builtin_bit_cast(unsigned, b); }
; DI float sigm_f(float x) { return __builtin_amdgcn_rcpf(1.f + __builtin_amdgcn_exp2f(-1.4426950408889634f * x)); }
; DI float silu_f(float x) { return x * sigm_f(x); }
;     DI void operator()(const f32x4 (&acc)[2][2][4][2], const Unit& u, int wr, int wc, int fr, int fq) const {
;         const int row0 = u.pm * BM + wr * 64 + fr, col0 = u.pn * HALF + wc * 32 + 8 * fq;
; #pragma unroll
;         for (int ai = 0; ai < 2; ++ai)
; #pragma unroll
;             for (int m = 0; m < 4; ++m) { bf16_t* rowp = G + (size_t)(row0 + ai * HALF + m * 16) * DFF + col0;
;                 f32x4 v0, v1;
; #pragma unroll
;                 for (int j = 0; j < 4; ++j) { v0[j] = silu_f(acc[ai][0][m][0][j]) * acc[ai][1][m][0][j]; v1[j] = silu_f(acc[ai][0][m][1][j]) * acc[ai][1][m][1][j]; }
;                 u32x4 w; w.x = cvtpk(v0[0], v0[1]); w.y = cvtpk(v0[2], v0[3]); w.z = cvtpk(v1[0], v1[1]); w.w = cvtpk(v1[2], v1[3]);
;                 *(u32x4*)rowp = w; }
.LBB0_298:
	v_mul_f32_e32 v145, 0xbfb8aa3b, v124
	v_exp_f32_e32 v145, v145
	v_lshl_or_b32 v146, s2, 7, v142
	v_lshl_add_u32 v144, s22, 8, v140
	v_ashrrev_i32_e32 v147, 31, v146
	v_add_f32_e32 v145, 1.0, v145
	v_rcp_f32_e32 v150, v145
	v_mul_f32_e32 v145, 0xbfb8aa3b, v116
	v_exp_f32_e32 v145, v145
	v_mov_b64_e32 v[138:139], s[10:11]
	v_mad_i64_i32 v[148:149], s[22:23], v144, s66, v[138:139]
	v_add_f32_e32 v145, 1.0, v145
	v_rcp_f32_e32 v152, v145
	v_mul_f32_e32 v145, 0xbfb8aa3b, v125
	v_exp_f32_e32 v145, v145
	s_andn2_b64 vcc, exec, s[6:7]
	v_add_f32_e32 v145, 1.0, v145
	v_rcp_f32_e32 v151, v145
	s_nop 0
	v_mul_f32_e32 v124, v124, v150
	v_mul_f32_e32 v125, v125, v151
	s_nop 0
	v_mul_f32_e32 v120, v120, v124
	v_mul_f32_e32 v121, v121, v125
	v_mul_f32_e32 v124, 0xbfb8aa3b, v117
	v_exp_f32_e32 v124, v124
	s_nop 0
	v_add_f32_e32 v124, 1.0, v124
	v_rcp_f32_e32 v153, v124
	s_nop 0
	v_mul_f32_e32 v116, v116, v152
	v_mul_f32_e32 v117, v117, v153
	s_nop 0
	v_mul_f32_e32 v116, v112, v116
	v_mul_f32_e32 v117, v113, v117
	v_mul_f32_e32 v113, 0xbfb8aa3b, v118
	v_exp_f32_e32 v113, v113
	v_mul_f32_e32 v112, 0xbfb8aa3b, v126
	v_exp_f32_e32 v112, v112
	v_cvt_pk_bf16_f32 v116, v116, v117
	v_add_f32_e32 v113, 1.0, v113
	v_rcp_f32_e32 v124, v113
	v_mul_f32_e32 v113, 0xbfb8aa3b, v127
	v_exp_f32_e32 v113, v113
	v_add_f32_e32 v112, 1.0, v112
	v_rcp_f32_e32 v112, v112
	v_add_f32_e32 v113, 1.0, v113
	v_rcp_f32_e32 v113, v113
	s_nop 0
	v_mul_f32_e32 v112, v126, v112
	v_mul_f32_e32 v113, v127, v113
	s_nop 0
	v_mul_f32_e32 v122, v122, v112
	v_mul_f32_e32 v123, v123, v113
	v_mul_f32_e32 v112, 0xbfb8aa3b, v119
	v_exp_f32_e32 v112, v112
	s_nop 0
	v_add_f32_e32 v112, 1.0, v112
	v_rcp_f32_e32 v125, v112
	s_nop 0
	v_mul_f32_e32 v112, v118, v124
	v_mul_f32_e32 v113, v119, v125
	s_nop 0
	v_mul_f32_e32 v118, v114, v112
	v_mul_f32_e32 v119, v115, v113
	v_lshlrev_b64 v[112:113], 1, v[146:147]
	v_lshl_add_u64 v[124:125], v[148:149], 0, v[112:113]
	v_cvt_pk_bf16_f32 v114, v120, v121
	v_cvt_pk_bf16_f32 v115, v122, v123
	v_cvt_pk_bf16_f32 v117, v118, v119
	global_store_dwordx4 v[124:125], v[114:117], off
	s_nop 1
	v_mul_f32_e32 v117, 0xbfb8aa3b, v100
	v_exp_f32_e32 v117, v117
	v_mul_f32_e32 v116, 0xbfb8aa3b, v108
	v_exp_f32_e32 v116, v116
	v_or_b32_e32 v114, 16, v144
	v_add_f32_e32 v117, 1.0, v117
	v_rcp_f32_e32 v118, v117
	v_mul_f32_e32 v117, 0xbfb8aa3b, v109
	v_exp_f32_e32 v117, v117
	v_add_f32_e32 v116, 1.0, v116
	v_rcp_f32_e32 v116, v116
	v_mad_i64_i32 v[114:115], s[22:23], v114, s66, v[138:139]
	v_add_f32_e32 v117, 1.0, v117
	v_rcp_f32_e32 v117, v117
	s_nop 0
	v_mul_f32_e32 v108, v108, v116
	v_mul_f32_e32 v109, v109, v117
	s_nop 0
	v_mul_f32_e32 v104, v104, v108
	v_mul_f32_e32 v105, v105, v109
	v_mul_f32_e32 v108, 0xbfb8aa3b, v101
	v_exp_f32_e32 v108, v108
	s_nop 0
	v_add_f32_e32 v108, 1.0, v108
	v_rcp_f32_e32 v119, v108
	s_nop 0
	v_mul_f32_e32 v100, v100, v118
	v_mul_f32_e32 v101, v101, v119
	s_nop 0
	v_mul_f32_e32 v100, v96, v100
	v_mul_f32_e32 v101, v97, v101
	v_mul_f32_e32 v97, 0xbfb8aa3b, v102
	v_exp_f32_e32 v97, v97
	v_mul_f32_e32 v96, 0xbfb8aa3b, v110
	v_exp_f32_e32 v96, v96
	v_add_f32_e32 v97, 1.0, v97
	v_rcp_f32_e32 v108, v97
	v_mul_f32_e32 v97, 0xbfb8aa3b, v111
	v_exp_f32_e32 v97, v97
	v_add_f32_e32 v96, 1.0, v96
	v_rcp_f32_e32 v96, v96
	v_add_f32_e32 v97, 1.0, v97
	v_rcp_f32_e32 v97, v97
	s_nop 0
	v_mul_f32_e32 v96, v110, v96
	v_mul_f32_e32 v97, v111, v97
	s_nop 0
	v_mul_f32_e32 v106, v106, v96
	v_mul_f32_e32 v107, v107, v97
	v_mul_f32_e32 v96, 0xbfb8aa3b, v103
	v_exp_f32_e32 v96, v96
	s_nop 0
	v_add_f32_e32 v96, 1.0, v96
	v_rcp_f32_e32 v109, v96
	s_nop 0
	v_mul_f32_e32 v96, v102, v108
	v_mul_f32_e32 v97, v103, v109
	s_nop 0
	v_mul_f32_e32 v102, v98, v96
	v_mul_f32_e32 v103, v99, v97
	v_lshl_add_u64 v[108:109], v[114:115], 0, v[112:113]
	v_cvt_pk_bf16_f32 v96, v104, v105
	v_cvt_pk_bf16_f32 v97, v106, v107
	v_cvt_pk_bf16_f32 v98, v100, v101
	v_cvt_pk_bf16_f32 v99, v102, v103
	global_store_dwordx4 v[108:109], v[96:99], off
	s_nop 1
	v_mul_f32_e32 v99, 0xbfb8aa3b, v84
	v_exp_f32_e32 v99, v99
	v_mul_f32_e32 v98, 0xbfb8aa3b, v92
	v_exp_f32_e32 v98, v98
	v_or_b32_e32 v96, 32, v144
	v_add_f32_e32 v99, 1.0, v99
	v_rcp_f32_e32 v100, v99
	v_mul_f32_e32 v99, 0xbfb8aa3b, v93
	v_exp_f32_e32 v99, v99
	v_add_f32_e32 v98, 1.0, v98
	v_rcp_f32_e32 v98, v98
	v_mad_i64_i32 v[96:97], s[22:23], v96, s66, v[138:139]
	v_add_f32_e32 v99, 1.0, v99
	v_rcp_f32_e32 v99, v99
	s_nop 0
	v_mul_f32_e32 v92, v92, v98
	v_mul_f32_e32 v93, v93, v99
	s_nop 0
	v_mul_f32_e32 v88, v88, v92
	v_mul_f32_e32 v89, v89, v93
	v_mul_f32_e32 v92, 0xbfb8aa3b, v85
	v_exp_f32_e32 v92, v92
	s_nop 0
	v_add_f32_e32 v92, 1.0, v92
	v_rcp_f32_e32 v101, v92
	s_nop 0
	v_mul_f32_e32 v84, v84, v100
	v_mul_f32_e32 v85, v85, v101
	s_nop 0
	v_mul_f32_e32 v84, v80, v84
	v_mul_f32_e32 v85, v81, v85
	v_mul_f32_e32 v81, 0xbfb8aa3b, v86
	v_exp_f32_e32 v81, v81
	v_mul_f32_e32 v80, 0xbfb8aa3b, v94
	v_exp_f32_e32 v80, v80
	v_add_f32_e32 v81, 1.0, v81
	v_rcp_f32_e32 v92, v81
	v_mul_f32_e32 v81, 0xbfb8aa3b, v95
	v_exp_f32_e32 v81, v81
	v_add_f32_e32 v80, 1.0, v80
	v_rcp_f32_e32 v80, v80
	v_add_f32_e32 v81, 1.0, v81
	v_rcp_f32_e32 v81, v81
	s_nop 0
	v_mul_f32_e32 v80, v94, v80
	v_mul_f32_e32 v81, v95, v81
	s_nop 0
	v_mul_f32_e32 v90, v90, v80
	v_mul_f32_e32 v91, v91, v81
	v_mul_f32_e32 v80, 0xbfb8aa3b, v87
	v_exp_f32_e32 v80, v80
	s_nop 0
	v_add_f32_e32 v80, 1.0, v80
	v_rcp_f32_e32 v93, v80
	s_nop 0
	v_mul_f32_e32 v80, v86, v92
	v_mul_f32_e32 v81, v87, v93
	s_nop 0
	v_mul_f32_e32 v86, v82, v80
	v_mul_f32_e32 v87, v83, v81
	v_lshl_add_u64 v[92:93], v[96:97], 0, v[112:113]
	v_cvt_pk_bf16_f32 v80, v88, v89
	v_cvt_pk_bf16_f32 v81, v90, v91
; DI unsigned cvtpk(float lo, float hi) { f32x2_t v = {lo, hi}; bf16x2_t b = __builtin_convertvector(v, bf16x2_t); return __builtin_bit_cast(unsigned, b); }
; DI float sigm_f(float x) { return __builtin_amdgcn_rcpf(1.f + __builtin_amdgcn_exp2f(-1.4426950408889634f * x)); }
; DI float silu_f(float x) { return x * sigm_f(x); }
;     DI void operator()(const f32x4 (&acc)[2][2][4][2], const Unit& u, int wr, int wc, int fr, int fq) const {
;         const int row0 = u.pm * BM + wr * 64 + fr, col0 = u.pn * HALF + wc * 32 + 8 * fq;
; #pragma unroll
;         for (int ai = 0; ai < 2; ++ai)
; #pragma unroll
;             for (int m = 0; m < 4; ++m) { bf16_t* rowp = G + (size_t)(row0 + ai * HALF + m * 16) * DFF + col0;
;                 f32x4 v0, v1;
; #pragma unroll
;                 for (int j = 0; j < 4; ++j) { v0[j] = silu_f(acc[ai][0][m][0][j]) * acc[ai][1][m][0][j]; v1[j] = silu_f(acc[ai][0][m][1][j]) * acc[ai][1][m][1][j]; }
;                 u32x4 w; w.x = cvtpk(v0[0], v0[1]); w.y = cvtpk(v0[2], v0[3]); w.z = cvtpk(v1[0], v1[1]); w.w = cvtpk(v1[2], v1[3]);
;                 *(u32x4*)rowp = w; }
	v_cvt_pk_bf16_f32 v82, v84, v85
	v_cvt_pk_bf16_f32 v83, v86, v87
	global_store_dwordx4 v[92:93], v[80:83], off
	s_nop 1
	v_mul_f32_e32 v83, 0xbfb8aa3b, v68
	v_exp_f32_e32 v83, v83
	v_mul_f32_e32 v82, 0xbfb8aa3b, v76
	v_exp_f32_e32 v82, v82
	v_or_b32_e32 v80, 48, v144
	v_add_f32_e32 v83, 1.0, v83
	v_rcp_f32_e32 v84, v83
	v_mul_f32_e32 v83, 0xbfb8aa3b, v77
	v_exp_f32_e32 v83, v83
	v_add_f32_e32 v82, 1.0, v82
	v_rcp_f32_e32 v82, v82
	v_mad_i64_i32 v[80:81], s[22:23], v80, s66, v[138:139]
	v_add_f32_e32 v83, 1.0, v83
	v_rcp_f32_e32 v83, v83
	s_nop 0
	v_mul_f32_e32 v76, v76, v82
	v_mul_f32_e32 v77, v77, v83
	s_nop 0
	v_mul_f32_e32 v72, v72, v76
	v_mul_f32_e32 v73, v73, v77
	v_mul_f32_e32 v76, 0xbfb8aa3b, v69
	v_exp_f32_e32 v76, v76
	s_nop 0
	v_add_f32_e32 v76, 1.0, v76
	v_rcp_f32_e32 v85, v76
	s_nop 0
	v_mul_f32_e32 v68, v68, v84
	v_mul_f32_e32 v69, v69, v85
	s_nop 0
	v_mul_f32_e32 v68, v64, v68
	v_mul_f32_e32 v69, v65, v69
	v_mul_f32_e32 v65, 0xbfb8aa3b, v70
	v_exp_f32_e32 v65, v65
	v_mul_f32_e32 v64, 0xbfb8aa3b, v78
	v_exp_f32_e32 v64, v64
	v_add_f32_e32 v65, 1.0, v65
	v_rcp_f32_e32 v76, v65
	v_mul_f32_e32 v65, 0xbfb8aa3b, v79
	v_exp_f32_e32 v65, v65
	v_add_f32_e32 v64, 1.0, v64
	v_rcp_f32_e32 v64, v64
	v_add_f32_e32 v65, 1.0, v65
	v_rcp_f32_e32 v65, v65
	s_nop 0
	v_mul_f32_e32 v64, v78, v64
	v_mul_f32_e32 v65, v79, v65
	s_nop 0
	v_mul_f32_e32 v74, v74, v64
	v_mul_f32_e32 v75, v75, v65
	v_mul_f32_e32 v64, 0xbfb8aa3b, v71
	v_exp_f32_e32 v64, v64
	s_nop 0
	v_add_f32_e32 v64, 1.0, v64
	v_rcp_f32_e32 v77, v64
	s_nop 0
	v_mul_f32_e32 v64, v70, v76
	v_mul_f32_e32 v65, v71, v77
	s_nop 0
	v_mul_f32_e32 v70, v66, v64
	v_mul_f32_e32 v71, v67, v65
	v_lshl_add_u64 v[76:77], v[80:81], 0, v[112:113]
	v_cvt_pk_bf16_f32 v64, v72, v73
	v_cvt_pk_bf16_f32 v65, v74, v75
	v_cvt_pk_bf16_f32 v66, v68, v69
	v_cvt_pk_bf16_f32 v67, v70, v71
	global_store_dwordx4 v[76:77], v[64:67], off
	s_nop 1
	v_mul_f32_e32 v67, 0xbfb8aa3b, v52
	v_exp_f32_e32 v67, v67
	v_mul_f32_e32 v66, 0xbfb8aa3b, v60
	v_exp_f32_e32 v66, v66
	v_add_u32_e32 v64, 0x80, v144
	v_add_f32_e32 v67, 1.0, v67
	v_rcp_f32_e32 v68, v67
	v_mul_f32_e32 v67, 0xbfb8aa3b, v61
	v_exp_f32_e32 v67, v67
	v_add_f32_e32 v66, 1.0, v66
	v_rcp_f32_e32 v66, v66
	v_mad_i64_i32 v[64:65], s[22:23], v64, s66, v[138:139]
	v_add_f32_e32 v67, 1.0, v67
	v_rcp_f32_e32 v67, v67
	s_nop 0
	v_mul_f32_e32 v60, v60, v66
	v_mul_f32_e32 v61, v61, v67
	s_nop 0
	v_mul_f32_e32 v56, v56, v60
	v_mul_f32_e32 v57, v57, v61
	v_mul_f32_e32 v60, 0xbfb8aa3b, v53
	v_exp_f32_e32 v60, v60
	s_nop 0
	v_add_f32_e32 v60, 1.0, v60
	v_rcp_f32_e32 v69, v60
	s_nop 0
	v_mul_f32_e32 v52, v52, v68
	v_mul_f32_e32 v53, v53, v69
	s_nop 0
	v_mul_f32_e32 v52, v48, v52
	v_mul_f32_e32 v53, v49, v53
	v_mul_f32_e32 v49, 0xbfb8aa3b, v54
	v_exp_f32_e32 v49, v49
	v_mul_f32_e32 v48, 0xbfb8aa3b, v62
	v_exp_f32_e32 v48, v48
	v_add_f32_e32 v49, 1.0, v49
	v_rcp_f32_e32 v60, v49
	v_mul_f32_e32 v49, 0xbfb8aa3b, v63
	v_exp_f32_e32 v49, v49
	v_add_f32_e32 v48, 1.0, v48
	v_rcp_f32_e32 v48, v48
	v_add_f32_e32 v49, 1.0, v49
	v_rcp_f32_e32 v49, v49
	s_nop 0
	v_mul_f32_e32 v48, v62, v48
	v_mul_f32_e32 v49, v63, v49
	s_nop 0
	v_mul_f32_e32 v58, v58, v48
	v_mul_f32_e32 v59, v59, v49
	v_mul_f32_e32 v48, 0xbfb8aa3b, v55
	v_exp_f32_e32 v48, v48
	s_nop 0
	v_add_f32_e32 v48, 1.0, v48
	v_rcp_f32_e32 v61, v48
	s_nop 0
	v_mul_f32_e32 v48, v54, v60
	v_mul_f32_e32 v49, v55, v61
	s_nop 0
	v_mul_f32_e32 v54, v50, v48
	v_mul_f32_e32 v55, v51, v49
	v_lshl_add_u64 v[60:61], v[64:65], 0, v[112:113]
	v_cvt_pk_bf16_f32 v48, v56, v57
	v_cvt_pk_bf16_f32 v49, v58, v59
	v_cvt_pk_bf16_f32 v50, v52, v53
	v_cvt_pk_bf16_f32 v51, v54, v55
	global_store_dwordx4 v[60:61], v[48:51], off
	s_nop 1
	v_mul_f32_e32 v51, 0xbfb8aa3b, v36
	v_exp_f32_e32 v51, v51
	v_mul_f32_e32 v50, 0xbfb8aa3b, v44
	v_exp_f32_e32 v50, v50
	v_add_u32_e32 v48, 0x90, v144
	v_add_f32_e32 v51, 1.0, v51
	v_rcp_f32_e32 v52, v51
	v_mul_f32_e32 v51, 0xbfb8aa3b, v45
	v_exp_f32_e32 v51, v51
	v_add_f32_e32 v50, 1.0, v50
	v_rcp_f32_e32 v50, v50
	v_mad_i64_i32 v[48:49], s[22:23], v48, s66, v[138:139]
	v_add_f32_e32 v51, 1.0, v51
	v_rcp_f32_e32 v51, v51
	s_nop 0
	v_mul_f32_e32 v44, v44, v50
	v_mul_f32_e32 v45, v45, v51
	s_nop 0
	v_mul_f32_e32 v40, v40, v44
	v_mul_f32_e32 v41, v41, v45
	v_mul_f32_e32 v44, 0xbfb8aa3b, v37
	v_exp_f32_e32 v44, v44
	s_nop 0
	v_add_f32_e32 v44, 1.0, v44
	v_rcp_f32_e32 v53, v44
	s_nop 0
	v_mul_f32_e32 v36, v36, v52
	v_mul_f32_e32 v37, v37, v53
	s_nop 0
	v_mul_f32_e32 v36, v32, v36
	v_mul_f32_e32 v37, v33, v37
	v_mul_f32_e32 v33, 0xbfb8aa3b, v38
; DI unsigned cvtpk(float lo, float hi) { f32x2_t v = {lo, hi}; bf16x2_t b = __builtin_convertvector(v, bf16x2_t); return __builtin_bit_cast(unsigned, b); }
; DI float silu_f(float x) { return x * sigm_f(x); }
; #define PG8_BAR __builtin_amdgcn_s_barrier()
;     DI void operator()(const f32x4 (&acc)[2][2][4][2], const Unit& u, int wr, int wc, int fr, int fq) const {
;         const int row0 = u.pm * BM + wr * 64 + fr, col0 = u.pn * HALF + wc * 32 + 8 * fq;
; #pragma unroll
;         for (int ai = 0; ai < 2; ++ai)
; #pragma unroll
;             for (int m = 0; m < 4; ++m) { bf16_t* rowp = G + (size_t)(row0 + ai * HALF + m * 16) * DFF + col0;
;                 f32x4 v0, v1;
; #pragma unroll
;                 for (int j = 0; j < 4; ++j) { v0[j] = silu_f(acc[ai][0][m][0][j]) * acc[ai][1][m][0][j]; v1[j] = silu_f(acc[ai][0][m][1][j]) * acc[ai][1][m][1][j]; }
;                 u32x4 w; w.x = cvtpk(v0[0], v0[1]); w.y = cvtpk(v0[2], v0[3]); w.z = cvtpk(v1[0], v1[1]); w.w = cvtpk(v1[2], v1[3]);
;                 *(u32x4*)rowp = w; }
; template <class Epi, bool ALIGN_EPI = true>
; DI void gemm_phase(int tb_, LAS unsigned char* lds, const Gemm g, const Sched& S, const Epi& E) {
;     ...
;                     for (int n = 0; n < 2; ++n) acc[a][b][m][n] = (f32x4){0.f, 0.f, 0.f, 0.f};
;         cur = nxt; cA = nA; cB = nB; ++ui;
;         if constexpr (ALIGN_EPI) { if (wr == 1) PG8_BAR; }
	v_exp_f32_e32 v33, v33
	v_mul_f32_e32 v32, 0xbfb8aa3b, v46
	v_exp_f32_e32 v32, v32
	v_add_f32_e32 v33, 1.0, v33
	v_rcp_f32_e32 v44, v33
	v_mul_f32_e32 v33, 0xbfb8aa3b, v47
	v_exp_f32_e32 v33, v33
	v_add_f32_e32 v32, 1.0, v32
	v_rcp_f32_e32 v32, v32
	v_add_f32_e32 v33, 1.0, v33
	v_rcp_f32_e32 v33, v33
	s_nop 0
	v_mul_f32_e32 v32, v46, v32
	v_mul_f32_e32 v33, v47, v33
	s_nop 0
	v_mul_f32_e32 v42, v42, v32
	v_mul_f32_e32 v43, v43, v33
	v_mul_f32_e32 v32, 0xbfb8aa3b, v39
	v_exp_f32_e32 v32, v32
	s_nop 0
	v_add_f32_e32 v32, 1.0, v32
	v_rcp_f32_e32 v45, v32
	s_nop 0
	v_mul_f32_e32 v32, v38, v44
	v_mul_f32_e32 v33, v39, v45
	s_nop 0
	v_mul_f32_e32 v38, v34, v32
	v_mul_f32_e32 v39, v35, v33
	v_lshl_add_u64 v[44:45], v[48:49], 0, v[112:113]
	v_cvt_pk_bf16_f32 v32, v40, v41
	v_cvt_pk_bf16_f32 v33, v42, v43
	v_cvt_pk_bf16_f32 v34, v36, v37
	v_cvt_pk_bf16_f32 v35, v38, v39
	global_store_dwordx4 v[44:45], v[32:35], off
	s_nop 1
	v_mul_f32_e32 v35, 0xbfb8aa3b, v20
	v_exp_f32_e32 v35, v35
	v_mul_f32_e32 v34, 0xbfb8aa3b, v28
	v_exp_f32_e32 v34, v34
	v_add_u32_e32 v32, 0xa0, v144
	v_add_f32_e32 v35, 1.0, v35
	v_rcp_f32_e32 v36, v35
	v_mul_f32_e32 v35, 0xbfb8aa3b, v29
	v_exp_f32_e32 v35, v35
	v_add_f32_e32 v34, 1.0, v34
	v_rcp_f32_e32 v34, v34
	v_mad_i64_i32 v[32:33], s[22:23], v32, s66, v[138:139]
	v_add_f32_e32 v35, 1.0, v35
	v_rcp_f32_e32 v35, v35
	s_nop 0
	v_mul_f32_e32 v28, v28, v34
	v_mul_f32_e32 v29, v29, v35
	s_nop 0
	v_mul_f32_e32 v24, v24, v28
	v_mul_f32_e32 v25, v25, v29
	v_mul_f32_e32 v28, 0xbfb8aa3b, v21
	v_exp_f32_e32 v28, v28
	s_nop 0
	v_add_f32_e32 v28, 1.0, v28
	v_rcp_f32_e32 v37, v28
	s_nop 0
	v_mul_f32_e32 v20, v20, v36
	v_mul_f32_e32 v21, v21, v37
	s_nop 0
	v_mul_f32_e32 v20, v16, v20
	v_mul_f32_e32 v21, v17, v21
	v_mul_f32_e32 v17, 0xbfb8aa3b, v22
	v_exp_f32_e32 v17, v17
	v_mul_f32_e32 v16, 0xbfb8aa3b, v30
	v_exp_f32_e32 v16, v16
	v_add_f32_e32 v17, 1.0, v17
	v_rcp_f32_e32 v28, v17
	v_mul_f32_e32 v17, 0xbfb8aa3b, v31
	v_exp_f32_e32 v17, v17
	v_add_f32_e32 v16, 1.0, v16
	v_rcp_f32_e32 v16, v16
	v_add_f32_e32 v17, 1.0, v17
	v_rcp_f32_e32 v17, v17
	s_nop 0
	v_mul_f32_e32 v16, v30, v16
	v_mul_f32_e32 v17, v31, v17
	s_nop 0
	v_mul_f32_e32 v26, v26, v16
	v_mul_f32_e32 v27, v27, v17
	v_mul_f32_e32 v16, 0xbfb8aa3b, v23
	v_exp_f32_e32 v16, v16
	s_nop 0
	v_add_f32_e32 v16, 1.0, v16
	v_rcp_f32_e32 v29, v16
	s_nop 0
	v_mul_f32_e32 v16, v22, v28
	v_mul_f32_e32 v17, v23, v29
	s_nop 0
	v_mul_f32_e32 v22, v18, v16
	v_mul_f32_e32 v23, v19, v17
	v_lshl_add_u64 v[28:29], v[32:33], 0, v[112:113]
	v_cvt_pk_bf16_f32 v16, v24, v25
	v_cvt_pk_bf16_f32 v17, v26, v27
	v_cvt_pk_bf16_f32 v18, v20, v21
	v_cvt_pk_bf16_f32 v19, v22, v23
	global_store_dwordx4 v[28:29], v[16:19], off
	s_nop 1
	v_mul_f32_e32 v19, 0xbfb8aa3b, v4
	v_exp_f32_e32 v19, v19
	v_mul_f32_e32 v18, 0xbfb8aa3b, v12
	v_exp_f32_e32 v18, v18
	v_add_u32_e32 v16, 0xb0, v144
	v_add_f32_e32 v19, 1.0, v19
	v_rcp_f32_e32 v20, v19
	v_mul_f32_e32 v19, 0xbfb8aa3b, v13
	v_exp_f32_e32 v19, v19
	v_add_f32_e32 v18, 1.0, v18
	v_rcp_f32_e32 v18, v18
	v_mad_i64_i32 v[16:17], s[22:23], v16, s66, v[138:139]
	v_add_f32_e32 v19, 1.0, v19
	v_rcp_f32_e32 v19, v19
	s_mov_b64 s[22:23], -1
	v_mul_f32_e32 v12, v12, v18
	v_mul_f32_e32 v13, v13, v19
	s_nop 0
	v_mul_f32_e32 v8, v8, v12
	v_mul_f32_e32 v9, v9, v13
	v_mul_f32_e32 v12, 0xbfb8aa3b, v5
	v_exp_f32_e32 v12, v12
	s_nop 0
	v_add_f32_e32 v12, 1.0, v12
	v_rcp_f32_e32 v21, v12
	s_nop 0
	v_mul_f32_e32 v4, v4, v20
	v_mul_f32_e32 v5, v5, v21
	s_nop 0
	v_mul_f32_e32 v4, v0, v4
	v_mul_f32_e32 v5, v1, v5
	v_mul_f32_e32 v1, 0xbfb8aa3b, v6
	v_exp_f32_e32 v1, v1
	v_mul_f32_e32 v0, 0xbfb8aa3b, v14
	v_exp_f32_e32 v0, v0
	v_add_f32_e32 v1, 1.0, v1
	v_rcp_f32_e32 v12, v1
	v_mul_f32_e32 v1, 0xbfb8aa3b, v15
	v_exp_f32_e32 v1, v1
	v_add_f32_e32 v0, 1.0, v0
	v_rcp_f32_e32 v0, v0
	v_add_f32_e32 v1, 1.0, v1
	v_rcp_f32_e32 v1, v1
	s_nop 0
	v_mul_f32_e32 v0, v14, v0
	v_mul_f32_e32 v1, v15, v1
	s_nop 0
	v_mul_f32_e32 v10, v10, v0
	v_mul_f32_e32 v11, v11, v1
	v_mul_f32_e32 v0, 0xbfb8aa3b, v7
	v_exp_f32_e32 v0, v0
	s_nop 0
	v_add_f32_e32 v0, 1.0, v0
	v_rcp_f32_e32 v13, v0
	s_nop 0
	v_mul_f32_e32 v0, v6, v12
	v_mul_f32_e32 v1, v7, v13
	s_nop 0
	v_mul_f32_e32 v6, v2, v0
	v_mul_f32_e32 v7, v3, v1
	v_lshl_add_u64 v[12:13], v[16:17], 0, v[112:113]
	v_cvt_pk_bf16_f32 v0, v8, v9
	v_cvt_pk_bf16_f32 v1, v10, v11
	v_cvt_pk_bf16_f32 v2, v4, v5
	v_cvt_pk_bf16_f32 v3, v6, v7
	global_store_dwordx4 v[12:13], v[0:3], off
	s_cbranch_vccnz .LBB0_291
	s_andn2_b64 vcc, exec, s[8:9]
	s_cbranch_vccnz .LBB0_290
	s_barrier
	s_branch .LBB0_290

; #define AT_STORE(bf) do { *(u32x4*)(Kl + (bf) * AT_KB + kkey0 * AT_KP + kc0 * 16) = kr0; if (k1ok) *(u32x4*)(Kl + (bf) * AT_KB + kkey1 * AT_KP + kc1 * 16) = kr1; \
;         *(u32x2*)(Vl + (bf) * AT_VB + vd * AT_VP + vc * 16) = (u32x2){vr.x, vr.y}; *(u32x2*)(Vl + (bf) * AT_VB + vd * AT_VP + vc * 16 + 8) = (u32x2){vr.z, vr.w}; } while (0)
; DI void attn_unit(int tb_, char* shm, const bf16_t* Qp, const bf16_t* Kp, const bf16_t* Vtp, int nkeys, int nrows, bf16_t* Op) {
;     ...
;             __builtin_amdgcn_sched_barrier(0);
;             const char* vb = Vl + bf * AT_VB + r32 * AT_VP + 8 * hi;
; #pragma unroll
;             for (int kh = 0; kh < 2; ++kh) {
;                 u32x2 va0[2], va1[2], vc0[2], vc1[2];
; #pragma unroll
;                 for (int k2 = 0; k2 < 2; ++k2) { const int ks = 2 * kh + k2; va0[k2] = *(const u32x2*)(vb + 32 * ks); va1[k2] = *(const u32x2*)(vb + 32 * ks + 16); vc0[k2] = *(const u32x2*)(vb + 32 * AT_VP + 32 * ks); vc1[k2] = *(const u32x2*)(vb + 32 * AT_VP + 32 * ks + 16); }
; #pragma unroll
;                 for (int k2 = 0; k2 < 2; ++k2) { const int ks = 2 * kh + k2;
;                     const bf16x8 vfa = __builtin_bit_cast(bf16x8, ((u32x4){va0[k2].x, va0[k2].y, va1[k2].x, va1[k2].y})), vfc = __builtin_bit_cast(bf16x8, ((u32x4){vc0[k2].x, vc0[k2].y, vc1[k2].x, vc1[k2].y}));
;                     oa0 = __builtin_amdgcn_mfma_f32_32x32x16_bf16(qa[ks], vfa, oa0, 0, 0, 0); oa1 = __builtin_amdgcn_mfma_f32_32x32x16_bf16(qa[ks], vfc, oa1, 0, 0, 0);
;                     ob0 = __builtin_amdgcn_mfma_f32_32x32x16_bf16(qb4[ks], vfa, ob0, 0, 0, 0); ob1 = __builtin_amdgcn_mfma_f32_32x32x16_bf16(qb4[ks], vfc, ob1, 0, 0, 0); }
;                 __builtin_amdgcn_sched_barrier(0);
;             }
;         }
;         if (t + 1 < nt) AT_STORE(bf ^ 1);
.Lat_val_skip:
	s_waitcnt lgkmcnt(0)
	s_barrier
	s_setprio 1
	s_and_b32 s37, s36, 1
	s_andn2_b64 vcc, exec, s[18:19]
	s_cbranch_vccnz .Lat_mm_skip
	s_mul_i32 s20, s37, 0x2200
	v_add_u32_e32 v84, s20, v204
	v_add_u32_e32 v88, 0x6800, v84
	v_add_u32_e32 v89, 0x7800, v84
	ds_read2_b64 v[80:83], v88 offset1:2
	ds_read2_b64 v[84:87], v89 offset0:32 offset1:34
	s_waitcnt lgkmcnt(1)
	v_mfma_f32_32x32x16_bf16 v[32:47], v[100:103], v[80:83], v[32:47]
	s_waitcnt lgkmcnt(0)
	v_mfma_f32_32x32x16_bf16 v[48:63], v[100:103], v[84:87], v[48:63]
	v_mfma_f32_32x32x16_bf16 v[16:31], v[64:67], v[80:83], v[16:31]
	ds_read2_b64 v[80:83], v89 offset0:36 offset1:38
	v_mfma_f32_32x32x16_bf16 v[0:15], v[64:67], v[84:87], v[0:15]
	ds_read2_b64 v[64:67], v88 offset0:4 offset1:6
	s_waitcnt lgkmcnt(0)
	v_mfma_f32_32x32x16_bf16 v[32:47], v[108:111], v[64:67], v[32:47]
	v_mfma_f32_32x32x16_bf16 v[48:63], v[108:111], v[80:83], v[48:63]
	v_mfma_f32_32x32x16_bf16 v[16:31], v[72:75], v[64:67], v[16:31]
	v_mfma_f32_32x32x16_bf16 v[0:15], v[72:75], v[80:83], v[0:15]
	ds_read2_b64 v[64:67], v88 offset0:8 offset1:10
	ds_read2_b64 v[72:75], v89 offset0:40 offset1:42
	s_waitcnt lgkmcnt(1)
	v_mfma_f32_32x32x16_bf16 v[32:47], v[104:107], v[64:67], v[32:47]
	s_waitcnt lgkmcnt(0)
	v_mfma_f32_32x32x16_bf16 v[48:63], v[104:107], v[72:75], v[48:63]
	v_mfma_f32_32x32x16_bf16 v[16:31], v[68:71], v[64:67], v[16:31]
	ds_read2_b64 v[64:67], v88 offset0:12 offset1:14
	v_mfma_f32_32x32x16_bf16 v[0:15], v[68:71], v[72:75], v[0:15]
	ds_read2_b64 v[68:71], v89 offset0:44 offset1:46
	s_waitcnt lgkmcnt(1)
	v_mfma_f32_32x32x16_bf16 v[32:47], v[96:99], v[64:67], v[32:47]
	s_waitcnt lgkmcnt(0)
	v_mfma_f32_32x32x16_bf16 v[48:63], v[96:99], v[68:71], v[48:63]
	v_mfma_f32_32x32x16_bf16 v[16:31], v[76:79], v[64:67], v[16:31]
	v_mfma_f32_32x32x16_bf16 v[0:15], v[76:79], v[68:71], v[0:15]
	s_cmp_lt_u32 s36, s35
	s_cbranch_scc0 .Lat_mm_skip
	s_xor_b32 s20, s37, 1
	s_mulk_i32 s20, 0x3400
	v_add_u32_e32 v92, s20, v210
	ds_read_b128 v[64:67], v92
	ds_read_b128 v[80:83], v92 offset:32
	ds_read_b128 v[84:87], v92 offset:6656
	ds_read_b128 v[216:219], v92 offset:6688
	s_waitcnt lgkmcnt(3)
	v_mfma_f32_32x32x16_bf16 v[96:111], v[64:67], v[172:175], 0
	v_mfma_f32_32x32x16_bf16 v[64:79], v[64:67], v[148:151], 0
	s_waitcnt lgkmcnt(2)
	v_mfma_f32_32x32x16_bf16 v[96:111], v[80:83], v[168:171], v[96:111]
	v_mfma_f32_32x32x16_bf16 v[64:79], v[80:83], v[140:143], v[64:79]
	ds_read_b128 v[80:83], v92 offset:64
	ds_read_b128 v[88:91], v92 offset:96
	ds_read_b128 v[220:223], v92 offset:6720
	ds_read_b128 v[224:227], v92 offset:6752
	s_waitcnt lgkmcnt(3)
	v_mfma_f32_32x32x16_bf16 v[96:111], v[80:83], v[164:167], v[96:111]
	v_mfma_f32_32x32x16_bf16 v[64:79], v[80:83], v[144:147], v[64:79]
	s_waitcnt lgkmcnt(2)
	v_mfma_f32_32x32x16_bf16 v[96:111], v[88:91], v[160:163], v[96:111]
	v_mfma_f32_32x32x16_bf16 v[64:79], v[88:91], v[136:139], v[64:79]
	ds_read_b128 v[80:83], v92 offset:128
	ds_read_b128 v[88:91], v92 offset:160
	ds_read_b128 v[242:245], v92 offset:6784
	ds_read_b128 v[246:249], v92 offset:6816
	v_mfma_f32_32x32x16_bf16 v[112:127], v[84:87], v[172:175], 0
	s_waitcnt lgkmcnt(3)
	v_mfma_f32_32x32x16_bf16 v[96:111], v[80:83], v[156:159], v[96:111]
	v_mfma_f32_32x32x16_bf16 v[64:79], v[80:83], v[132:135], v[64:79]
	v_mfma_f32_32x32x16_bf16 v[112:127], v[216:219], v[168:171], v[112:127]
	s_waitcnt lgkmcnt(2)
	v_mfma_f32_32x32x16_bf16 v[96:111], v[88:91], v[152:155], v[96:111]
	v_mfma_f32_32x32x16_bf16 v[64:79], v[88:91], v[128:131], v[64:79]
	v_mfma_f32_32x32x16_bf16 v[80:95], v[84:87], v[148:151], 0
	v_mfma_f32_32x32x16_bf16 v[112:127], v[220:223], v[164:167], v[112:127]
	v_mfma_f32_32x32x16_bf16 v[80:95], v[216:219], v[140:143], v[80:95]
	v_mfma_f32_32x32x16_bf16 v[112:127], v[224:227], v[160:163], v[112:127]
	v_mfma_f32_32x32x16_bf16 v[80:95], v[220:223], v[144:147], v[80:95]
	s_waitcnt lgkmcnt(1)
	v_mfma_f32_32x32x16_bf16 v[112:127], v[242:245], v[156:159], v[112:127]
	v_mfma_f32_32x32x16_bf16 v[80:95], v[224:227], v[136:139], v[80:95]
	s_waitcnt lgkmcnt(0)
	v_mfma_f32_32x32x16_bf16 v[112:127], v[246:249], v[152:155], v[112:127]
	v_mfma_f32_32x32x16_bf16 v[80:95], v[242:245], v[132:135], v[80:95]
	v_mfma_f32_32x32x16_bf16 v[80:95], v[246:249], v[128:131], v[80:95]
.Lat_mm_skip:
	s_setprio 0
	s_mul_i32 s38, s37, 0x3400
	s_waitcnt vmcnt(0)
	v_add3_u32 v216, s38, v205, v206
	ds_write_b128 v216, v[184:187]
	s_and_saveexec_b64 s[20:21], s[8:9]
	v_add3_u32 v216, s38, v208, v207
	ds_write_b128 v216, v[176:179]
	s_or_b64 exec, exec, s[20:21]
	s_xor_b32 s38, s37, 1
	s_mulk_i32 s38, 0x2200
	v_add_u32_e32 v216, s38, v209
	v_add_u32_e32 v216, 0x6800, v216
	ds_write2_b64 v216, v[180:181], v[182:183] offset1:1
	global_load_dwordx4 v[184:187], v[196:197], off
	s_and_saveexec_b64 s[10:11], s[8:9]
	s_cbranch_execz .Lat_k1
	global_load_dwordx4 v[176:179], v[192:193], off

; DI unsigned cvtpk(float lo, float hi) { f32x2_t v = {lo, hi}; bf16x2_t b = __builtin_convertvector(v, bf16x2_t); return __builtin_bit_cast(unsigned, b); }
; DI float sigm_f(float x) { return __builtin_amdgcn_rcpf(1.f + __builtin_amdgcn_exp2f(-1.4426950408889634f * x)); }
; DI float silu_f(float x) { return x * sigm_f(x); }
;     DI void operator()(const f32x4 (&acc)[2][2][4][2], const Unit& u, int wr, int wc, int fr, int fq) const {
;         const int row0 = u.pm * BM + wr * 64 + fr, col0 = u.pn * HALF + wc * 32 + 8 * fq;
; #pragma unroll
;         for (int ai = 0; ai < 2; ++ai)
; #pragma unroll
;             for (int m = 0; m < 4; ++m) { bf16_t* rowp = G + (size_t)(row0 + ai * HALF + m * 16) * DFF + col0;
;                 f32x4 v0, v1;
; #pragma unroll
;                 for (int j = 0; j < 4; ++j) { v0[j] = silu_f(acc[ai][0][m][0][j]) * acc[ai][1][m][0][j]; v1[j] = silu_f(acc[ai][0][m][1][j]) * acc[ai][1][m][1][j]; }
;                 u32x4 w; w.x = cvtpk(v0[0], v0[1]); w.y = cvtpk(v0[2], v0[3]); w.z = cvtpk(v1[0], v1[1]); w.w = cvtpk(v1[2], v1[3]);
;                 *(u32x4*)rowp = w; }
.LBB0_1997:
	v_mul_f32_e32 v145, 0xbfb8aa3b, v124
	v_exp_f32_e32 v145, v145
	v_lshl_or_b32 v146, s22, 7, v142
	v_lshl_add_u32 v144, s24, 8, v140
	v_ashrrev_i32_e32 v147, 31, v146
	v_add_f32_e32 v145, 1.0, v145
	v_rcp_f32_e32 v150, v145
	v_mul_f32_e32 v145, 0xbfb8aa3b, v116
	v_exp_f32_e32 v145, v145
	v_mov_b64_e32 v[138:139], s[10:11]
	v_mad_i64_i32 v[148:149], s[22:23], v144, s66, v[138:139]
	v_add_f32_e32 v145, 1.0, v145
	v_rcp_f32_e32 v152, v145
	v_mul_f32_e32 v145, 0xbfb8aa3b, v125
	v_exp_f32_e32 v145, v145
	s_andn2_b64 vcc, exec, s[6:7]
	v_add_f32_e32 v145, 1.0, v145
	v_rcp_f32_e32 v151, v145
	s_nop 0
	v_mul_f32_e32 v124, v124, v150
	v_mul_f32_e32 v125, v125, v151
	s_nop 0
	v_mul_f32_e32 v120, v120, v124
	v_mul_f32_e32 v121, v121, v125
	v_mul_f32_e32 v124, 0xbfb8aa3b, v117
	v_exp_f32_e32 v124, v124
	s_nop 0
	v_add_f32_e32 v124, 1.0, v124
	v_rcp_f32_e32 v153, v124
	s_nop 0
	v_mul_f32_e32 v116, v116, v152
	v_mul_f32_e32 v117, v117, v153
	s_nop 0
	v_mul_f32_e32 v116, v112, v116
	v_mul_f32_e32 v117, v113, v117
	v_mul_f32_e32 v113, 0xbfb8aa3b, v118
	v_exp_f32_e32 v113, v113
	v_mul_f32_e32 v112, 0xbfb8aa3b, v126
	v_exp_f32_e32 v112, v112
	v_cvt_pk_bf16_f32 v116, v116, v117
	v_add_f32_e32 v113, 1.0, v113
	v_rcp_f32_e32 v124, v113
	v_mul_f32_e32 v113, 0xbfb8aa3b, v127
	v_exp_f32_e32 v113, v113
	v_add_f32_e32 v112, 1.0, v112
	v_rcp_f32_e32 v112, v112
	v_add_f32_e32 v113, 1.0, v113
	v_rcp_f32_e32 v113, v113
	s_nop 0
	v_mul_f32_e32 v112, v126, v112
	v_mul_f32_e32 v113, v127, v113
	s_nop 0
	v_mul_f32_e32 v122, v122, v112
	v_mul_f32_e32 v123, v123, v113
	v_mul_f32_e32 v112, 0xbfb8aa3b, v119
	v_exp_f32_e32 v112, v112
	s_nop 0
	v_add_f32_e32 v112, 1.0, v112
	v_rcp_f32_e32 v125, v112
	s_nop 0
	v_mul_f32_e32 v112, v118, v124
	v_mul_f32_e32 v113, v119, v125
	s_nop 0
	v_mul_f32_e32 v118, v114, v112
	v_mul_f32_e32 v119, v115, v113
	v_lshlrev_b64 v[112:113], 1, v[146:147]
	v_lshl_add_u64 v[124:125], v[148:149], 0, v[112:113]
	v_cvt_pk_bf16_f32 v114, v120, v121
	v_cvt_pk_bf16_f32 v115, v122, v123
	v_cvt_pk_bf16_f32 v117, v118, v119
	global_store_dwordx4 v[124:125], v[114:117], off
	s_nop 1
	v_mul_f32_e32 v117, 0xbfb8aa3b, v100
	v_exp_f32_e32 v117, v117
	v_mul_f32_e32 v116, 0xbfb8aa3b, v108
	v_exp_f32_e32 v116, v116
	v_or_b32_e32 v114, 16, v144
	v_add_f32_e32 v117, 1.0, v117
	v_rcp_f32_e32 v118, v117
	v_mul_f32_e32 v117, 0xbfb8aa3b, v109
	v_exp_f32_e32 v117, v117
	v_add_f32_e32 v116, 1.0, v116
	v_rcp_f32_e32 v116, v116
	v_mad_i64_i32 v[114:115], s[22:23], v114, s66, v[138:139]
	v_add_f32_e32 v117, 1.0, v117
	v_rcp_f32_e32 v117, v117
	s_nop 0
	v_mul_f32_e32 v108, v108, v116
	v_mul_f32_e32 v109, v109, v117
	s_nop 0
	v_mul_f32_e32 v104, v104, v108
	v_mul_f32_e32 v105, v105, v109
	v_mul_f32_e32 v108, 0xbfb8aa3b, v101
	v_exp_f32_e32 v108, v108
	s_nop 0
	v_add_f32_e32 v108, 1.0, v108
	v_rcp_f32_e32 v119, v108
	s_nop 0
	v_mul_f32_e32 v100, v100, v118
	v_mul_f32_e32 v101, v101, v119
	s_nop 0
	v_mul_f32_e32 v100, v96, v100
	v_mul_f32_e32 v101, v97, v101
	v_mul_f32_e32 v97, 0xbfb8aa3b, v102
	v_exp_f32_e32 v97, v97
	v_mul_f32_e32 v96, 0xbfb8aa3b, v110
	v_exp_f32_e32 v96, v96
	v_add_f32_e32 v97, 1.0, v97
	v_rcp_f32_e32 v108, v97
	v_mul_f32_e32 v97, 0xbfb8aa3b, v111
	v_exp_f32_e32 v97, v97
	v_add_f32_e32 v96, 1.0, v96
	v_rcp_f32_e32 v96, v96
	v_add_f32_e32 v97, 1.0, v97
	v_rcp_f32_e32 v97, v97
	s_nop 0
	v_mul_f32_e32 v96, v110, v96
	v_mul_f32_e32 v97, v111, v97
	s_nop 0
	v_mul_f32_e32 v106, v106, v96
	v_mul_f32_e32 v107, v107, v97
	v_mul_f32_e32 v96, 0xbfb8aa3b, v103
	v_exp_f32_e32 v96, v96
	s_nop 0
	v_add_f32_e32 v96, 1.0, v96
	v_rcp_f32_e32 v109, v96
	s_nop 0
	v_mul_f32_e32 v96, v102, v108
	v_mul_f32_e32 v97, v103, v109
	s_nop 0
	v_mul_f32_e32 v102, v98, v96
	v_mul_f32_e32 v103, v99, v97
	v_lshl_add_u64 v[108:109], v[114:115], 0, v[112:113]
	v_cvt_pk_bf16_f32 v96, v104, v105
	v_cvt_pk_bf16_f32 v97, v106, v107
	v_cvt_pk_bf16_f32 v98, v100, v101
	v_cvt_pk_bf16_f32 v99, v102, v103
	global_store_dwordx4 v[108:109], v[96:99], off
	s_nop 1
	v_mul_f32_e32 v99, 0xbfb8aa3b, v84
	v_exp_f32_e32 v99, v99
	v_mul_f32_e32 v98, 0xbfb8aa3b, v92
	v_exp_f32_e32 v98, v98
	v_or_b32_e32 v96, 32, v144
	v_add_f32_e32 v99, 1.0, v99
	v_rcp_f32_e32 v100, v99
	v_mul_f32_e32 v99, 0xbfb8aa3b, v93
	v_exp_f32_e32 v99, v99
	v_add_f32_e32 v98, 1.0, v98
	v_rcp_f32_e32 v98, v98
	v_mad_i64_i32 v[96:97], s[22:23], v96, s66, v[138:139]
	v_add_f32_e32 v99, 1.0, v99
	v_rcp_f32_e32 v99, v99
	s_nop 0
	v_mul_f32_e32 v92, v92, v98
	v_mul_f32_e32 v93, v93, v99
	s_nop 0
	v_mul_f32_e32 v88, v88, v92
	v_mul_f32_e32 v89, v89, v93
	v_mul_f32_e32 v92, 0xbfb8aa3b, v85
	v_exp_f32_e32 v92, v92
	s_nop 0
	v_add_f32_e32 v92, 1.0, v92
	v_rcp_f32_e32 v101, v92
	s_nop 0
	v_mul_f32_e32 v84, v84, v100
	v_mul_f32_e32 v85, v85, v101
	s_nop 0
	v_mul_f32_e32 v84, v80, v84
	v_mul_f32_e32 v85, v81, v85
	v_mul_f32_e32 v81, 0xbfb8aa3b, v86
	v_exp_f32_e32 v81, v81
	v_mul_f32_e32 v80, 0xbfb8aa3b, v94
	v_exp_f32_e32 v80, v80
	v_add_f32_e32 v81, 1.0, v81
	v_rcp_f32_e32 v92, v81
	v_mul_f32_e32 v81, 0xbfb8aa3b, v95
	v_exp_f32_e32 v81, v81
	v_add_f32_e32 v80, 1.0, v80
	v_rcp_f32_e32 v80, v80
	v_add_f32_e32 v81, 1.0, v81
	v_rcp_f32_e32 v81, v81
	s_nop 0
	v_mul_f32_e32 v80, v94, v80
	v_mul_f32_e32 v81, v95, v81
	s_nop 0
	v_mul_f32_e32 v90, v90, v80
	v_mul_f32_e32 v91, v91, v81
	v_mul_f32_e32 v80, 0xbfb8aa3b, v87
	v_exp_f32_e32 v80, v80
	s_nop 0
	v_add_f32_e32 v80, 1.0, v80
	v_rcp_f32_e32 v93, v80
	s_nop 0
	v_mul_f32_e32 v80, v86, v92
	v_mul_f32_e32 v81, v87, v93
	s_nop 0
	v_mul_f32_e32 v86, v82, v80
	v_mul_f32_e32 v87, v83, v81
	v_lshl_add_u64 v[92:93], v[96:97], 0, v[112:113]
	v_cvt_pk_bf16_f32 v80, v88, v89
	v_cvt_pk_bf16_f32 v81, v90, v91
; DI unsigned cvtpk(float lo, float hi) { f32x2_t v = {lo, hi}; bf16x2_t b = __builtin_convertvector(v, bf16x2_t); return __builtin_bit_cast(unsigned, b); }
; DI float sigm_f(float x) { return __builtin_amdgcn_rcpf(1.f + __builtin_amdgcn_exp2f(-1.4426950408889634f * x)); }
; DI float silu_f(float x) { return x * sigm_f(x); }
;     DI void operator()(const f32x4 (&acc)[2][2][4][2], const Unit& u, int wr, int wc, int fr, int fq) const {
;         const int row0 = u.pm * BM + wr * 64 + fr, col0 = u.pn * HALF + wc * 32 + 8 * fq;
; #pragma unroll
;         for (int ai = 0; ai < 2; ++ai)
; #pragma unroll
;             for (int m = 0; m < 4; ++m) { bf16_t* rowp = G + (size_t)(row0 + ai * HALF + m * 16) * DFF + col0;
;                 f32x4 v0, v1;
; #pragma unroll
;                 for (int j = 0; j < 4; ++j) { v0[j] = silu_f(acc[ai][0][m][0][j]) * acc[ai][1][m][0][j]; v1[j] = silu_f(acc[ai][0][m][1][j]) * acc[ai][1][m][1][j]; }
;                 u32x4 w; w.x = cvtpk(v0[0], v0[1]); w.y = cvtpk(v0[2], v0[3]); w.z = cvtpk(v1[0], v1[1]); w.w = cvtpk(v1[2], v1[3]);
;                 *(u32x4*)rowp = w; }
	v_cvt_pk_bf16_f32 v82, v84, v85
	v_cvt_pk_bf16_f32 v83, v86, v87
	global_store_dwordx4 v[92:93], v[80:83], off
	s_nop 1
	v_mul_f32_e32 v83, 0xbfb8aa3b, v68
	v_exp_f32_e32 v83, v83
	v_mul_f32_e32 v82, 0xbfb8aa3b, v76
	v_exp_f32_e32 v82, v82
	v_or_b32_e32 v80, 48, v144
	v_add_f32_e32 v83, 1.0, v83
	v_rcp_f32_e32 v84, v83
	v_mul_f32_e32 v83, 0xbfb8aa3b, v77
	v_exp_f32_e32 v83, v83
	v_add_f32_e32 v82, 1.0, v82
	v_rcp_f32_e32 v82, v82
	v_mad_i64_i32 v[80:81], s[22:23], v80, s66, v[138:139]
	v_add_f32_e32 v83, 1.0, v83
	v_rcp_f32_e32 v83, v83
	s_nop 0
	v_mul_f32_e32 v76, v76, v82
	v_mul_f32_e32 v77, v77, v83
	s_nop 0
	v_mul_f32_e32 v72, v72, v76
	v_mul_f32_e32 v73, v73, v77
	v_mul_f32_e32 v76, 0xbfb8aa3b, v69
	v_exp_f32_e32 v76, v76
	s_nop 0
	v_add_f32_e32 v76, 1.0, v76
	v_rcp_f32_e32 v85, v76
	s_nop 0
	v_mul_f32_e32 v68, v68, v84
	v_mul_f32_e32 v69, v69, v85
	s_nop 0
	v_mul_f32_e32 v68, v64, v68
	v_mul_f32_e32 v69, v65, v69
	v_mul_f32_e32 v65, 0xbfb8aa3b, v70
	v_exp_f32_e32 v65, v65
	v_mul_f32_e32 v64, 0xbfb8aa3b, v78
	v_exp_f32_e32 v64, v64
	v_add_f32_e32 v65, 1.0, v65
	v_rcp_f32_e32 v76, v65
	v_mul_f32_e32 v65, 0xbfb8aa3b, v79
	v_exp_f32_e32 v65, v65
	v_add_f32_e32 v64, 1.0, v64
	v_rcp_f32_e32 v64, v64
	v_add_f32_e32 v65, 1.0, v65
	v_rcp_f32_e32 v65, v65
	s_nop 0
	v_mul_f32_e32 v64, v78, v64
	v_mul_f32_e32 v65, v79, v65
	s_nop 0
	v_mul_f32_e32 v74, v74, v64
	v_mul_f32_e32 v75, v75, v65
	v_mul_f32_e32 v64, 0xbfb8aa3b, v71
	v_exp_f32_e32 v64, v64
	s_nop 0
	v_add_f32_e32 v64, 1.0, v64
	v_rcp_f32_e32 v77, v64
	s_nop 0
	v_mul_f32_e32 v64, v70, v76
	v_mul_f32_e32 v65, v71, v77
	s_nop 0
	v_mul_f32_e32 v70, v66, v64
	v_mul_f32_e32 v71, v67, v65
	v_lshl_add_u64 v[76:77], v[80:81], 0, v[112:113]
	v_cvt_pk_bf16_f32 v64, v72, v73
	v_cvt_pk_bf16_f32 v65, v74, v75
	v_cvt_pk_bf16_f32 v66, v68, v69
	v_cvt_pk_bf16_f32 v67, v70, v71
	global_store_dwordx4 v[76:77], v[64:67], off
	s_nop 1
	v_mul_f32_e32 v67, 0xbfb8aa3b, v52
	v_exp_f32_e32 v67, v67
	v_mul_f32_e32 v66, 0xbfb8aa3b, v60
	v_exp_f32_e32 v66, v66
	v_add_u32_e32 v64, 0x80, v144
	v_add_f32_e32 v67, 1.0, v67
	v_rcp_f32_e32 v68, v67
	v_mul_f32_e32 v67, 0xbfb8aa3b, v61
	v_exp_f32_e32 v67, v67
	v_add_f32_e32 v66, 1.0, v66
	v_rcp_f32_e32 v66, v66
	v_mad_i64_i32 v[64:65], s[22:23], v64, s66, v[138:139]
	v_add_f32_e32 v67, 1.0, v67
	v_rcp_f32_e32 v67, v67
	s_nop 0
	v_mul_f32_e32 v60, v60, v66
	v_mul_f32_e32 v61, v61, v67
	s_nop 0
	v_mul_f32_e32 v56, v56, v60
	v_mul_f32_e32 v57, v57, v61
	v_mul_f32_e32 v60, 0xbfb8aa3b, v53
	v_exp_f32_e32 v60, v60
	s_nop 0
	v_add_f32_e32 v60, 1.0, v60
	v_rcp_f32_e32 v69, v60
	s_nop 0
	v_mul_f32_e32 v52, v52, v68
	v_mul_f32_e32 v53, v53, v69
	s_nop 0
	v_mul_f32_e32 v52, v48, v52
	v_mul_f32_e32 v53, v49, v53
	v_mul_f32_e32 v49, 0xbfb8aa3b, v54
	v_exp_f32_e32 v49, v49
	v_mul_f32_e32 v48, 0xbfb8aa3b, v62
	v_exp_f32_e32 v48, v48
	v_add_f32_e32 v49, 1.0, v49
	v_rcp_f32_e32 v60, v49
	v_mul_f32_e32 v49, 0xbfb8aa3b, v63
	v_exp_f32_e32 v49, v49
	v_add_f32_e32 v48, 1.0, v48
	v_rcp_f32_e32 v48, v48
	v_add_f32_e32 v49, 1.0, v49
	v_rcp_f32_e32 v49, v49
	s_nop 0
	v_mul_f32_e32 v48, v62, v48
	v_mul_f32_e32 v49, v63, v49
	s_nop 0
	v_mul_f32_e32 v58, v58, v48
	v_mul_f32_e32 v59, v59, v49
	v_mul_f32_e32 v48, 0xbfb8aa3b, v55
	v_exp_f32_e32 v48, v48
	s_nop 0
	v_add_f32_e32 v48, 1.0, v48
	v_rcp_f32_e32 v61, v48
	s_nop 0
	v_mul_f32_e32 v48, v54, v60
	v_mul_f32_e32 v49, v55, v61
	s_nop 0
	v_mul_f32_e32 v54, v50, v48
	v_mul_f32_e32 v55, v51, v49
	v_lshl_add_u64 v[60:61], v[64:65], 0, v[112:113]
	v_cvt_pk_bf16_f32 v48, v56, v57
	v_cvt_pk_bf16_f32 v49, v58, v59
	v_cvt_pk_bf16_f32 v50, v52, v53
	v_cvt_pk_bf16_f32 v51, v54, v55
	global_store_dwordx4 v[60:61], v[48:51], off
	s_nop 1
	v_mul_f32_e32 v51, 0xbfb8aa3b, v36
	v_exp_f32_e32 v51, v51
	v_mul_f32_e32 v50, 0xbfb8aa3b, v44
	v_exp_f32_e32 v50, v50
	v_add_u32_e32 v48, 0x90, v144
	v_add_f32_e32 v51, 1.0, v51
	v_rcp_f32_e32 v52, v51
	v_mul_f32_e32 v51, 0xbfb8aa3b, v45
	v_exp_f32_e32 v51, v51
	v_add_f32_e32 v50, 1.0, v50
	v_rcp_f32_e32 v50, v50
	v_mad_i64_i32 v[48:49], s[22:23], v48, s66, v[138:139]
	v_add_f32_e32 v51, 1.0, v51
	v_rcp_f32_e32 v51, v51
	s_nop 0
	v_mul_f32_e32 v44, v44, v50
	v_mul_f32_e32 v45, v45, v51
	s_nop 0
	v_mul_f32_e32 v40, v40, v44
	v_mul_f32_e32 v41, v41, v45
	v_mul_f32_e32 v44, 0xbfb8aa3b, v37
	v_exp_f32_e32 v44, v44
	s_nop 0
	v_add_f32_e32 v44, 1.0, v44
	v_rcp_f32_e32 v53, v44
	s_nop 0
	v_mul_f32_e32 v36, v36, v52
	v_mul_f32_e32 v37, v37, v53
	s_nop 0
	v_mul_f32_e32 v36, v32, v36
	v_mul_f32_e32 v37, v33, v37
	v_mul_f32_e32 v33, 0xbfb8aa3b, v38
; DI unsigned cvtpk(float lo, float hi) { f32x2_t v = {lo, hi}; bf16x2_t b = __builtin_convertvector(v, bf16x2_t); return __builtin_bit_cast(unsigned, b); }
; DI float silu_f(float x) { return x * sigm_f(x); }
; #define PG8_BAR __builtin_amdgcn_s_barrier()
;     DI void operator()(const f32x4 (&acc)[2][2][4][2], const Unit& u, int wr, int wc, int fr, int fq) const {
;         const int row0 = u.pm * BM + wr * 64 + fr, col0 = u.pn * HALF + wc * 32 + 8 * fq;
; #pragma unroll
;         for (int ai = 0; ai < 2; ++ai)
; #pragma unroll
;             for (int m = 0; m < 4; ++m) { bf16_t* rowp = G + (size_t)(row0 + ai * HALF + m * 16) * DFF + col0;
;                 f32x4 v0, v1;
; #pragma unroll
;                 for (int j = 0; j < 4; ++j) { v0[j] = silu_f(acc[ai][0][m][0][j]) * acc[ai][1][m][0][j]; v1[j] = silu_f(acc[ai][0][m][1][j]) * acc[ai][1][m][1][j]; }
;                 u32x4 w; w.x = cvtpk(v0[0], v0[1]); w.y = cvtpk(v0[2], v0[3]); w.z = cvtpk(v1[0], v1[1]); w.w = cvtpk(v1[2], v1[3]);
;                 *(u32x4*)rowp = w; }
; template <class Epi, bool ALIGN_EPI = true>
; DI void gemm_phase(int tb_, LAS unsigned char* lds, const Gemm g, const Sched& S, const Epi& E) {
;     ...
;                     for (int n = 0; n < 2; ++n) acc[a][b][m][n] = (f32x4){0.f, 0.f, 0.f, 0.f};
;         cur = nxt; cA = nA; cB = nB; ++ui;
;         if constexpr (ALIGN_EPI) { if (wr == 1) PG8_BAR; }
	v_exp_f32_e32 v33, v33
	v_mul_f32_e32 v32, 0xbfb8aa3b, v46
	v_exp_f32_e32 v32, v32
	v_add_f32_e32 v33, 1.0, v33
	v_rcp_f32_e32 v44, v33
	v_mul_f32_e32 v33, 0xbfb8aa3b, v47
	v_exp_f32_e32 v33, v33
	v_add_f32_e32 v32, 1.0, v32
	v_rcp_f32_e32 v32, v32
	v_add_f32_e32 v33, 1.0, v33
	v_rcp_f32_e32 v33, v33
	s_nop 0
	v_mul_f32_e32 v32, v46, v32
	v_mul_f32_e32 v33, v47, v33
	s_nop 0
	v_mul_f32_e32 v42, v42, v32
	v_mul_f32_e32 v43, v43, v33
	v_mul_f32_e32 v32, 0xbfb8aa3b, v39
	v_exp_f32_e32 v32, v32
	s_nop 0
	v_add_f32_e32 v32, 1.0, v32
	v_rcp_f32_e32 v45, v32
	s_nop 0
	v_mul_f32_e32 v32, v38, v44
	v_mul_f32_e32 v33, v39, v45
	s_nop 0
	v_mul_f32_e32 v38, v34, v32
	v_mul_f32_e32 v39, v35, v33
	v_lshl_add_u64 v[44:45], v[48:49], 0, v[112:113]
	v_cvt_pk_bf16_f32 v32, v40, v41
	v_cvt_pk_bf16_f32 v33, v42, v43
	v_cvt_pk_bf16_f32 v34, v36, v37
	v_cvt_pk_bf16_f32 v35, v38, v39
	global_store_dwordx4 v[44:45], v[32:35], off
	s_nop 1
	v_mul_f32_e32 v35, 0xbfb8aa3b, v20
	v_exp_f32_e32 v35, v35
	v_mul_f32_e32 v34, 0xbfb8aa3b, v28
	v_exp_f32_e32 v34, v34
	v_add_u32_e32 v32, 0xa0, v144
	v_add_f32_e32 v35, 1.0, v35
	v_rcp_f32_e32 v36, v35
	v_mul_f32_e32 v35, 0xbfb8aa3b, v29
	v_exp_f32_e32 v35, v35
	v_add_f32_e32 v34, 1.0, v34
	v_rcp_f32_e32 v34, v34
	v_mad_i64_i32 v[32:33], s[22:23], v32, s66, v[138:139]
	v_add_f32_e32 v35, 1.0, v35
	v_rcp_f32_e32 v35, v35
	s_nop 0
	v_mul_f32_e32 v28, v28, v34
	v_mul_f32_e32 v29, v29, v35
	s_nop 0
	v_mul_f32_e32 v24, v24, v28
	v_mul_f32_e32 v25, v25, v29
	v_mul_f32_e32 v28, 0xbfb8aa3b, v21
	v_exp_f32_e32 v28, v28
	s_nop 0
	v_add_f32_e32 v28, 1.0, v28
	v_rcp_f32_e32 v37, v28
	s_nop 0
	v_mul_f32_e32 v20, v20, v36
	v_mul_f32_e32 v21, v21, v37
	s_nop 0
	v_mul_f32_e32 v20, v16, v20
	v_mul_f32_e32 v21, v17, v21
	v_mul_f32_e32 v17, 0xbfb8aa3b, v22
	v_exp_f32_e32 v17, v17
	v_mul_f32_e32 v16, 0xbfb8aa3b, v30
	v_exp_f32_e32 v16, v16
	v_add_f32_e32 v17, 1.0, v17
	v_rcp_f32_e32 v28, v17
	v_mul_f32_e32 v17, 0xbfb8aa3b, v31
	v_exp_f32_e32 v17, v17
	v_add_f32_e32 v16, 1.0, v16
	v_rcp_f32_e32 v16, v16
	v_add_f32_e32 v17, 1.0, v17
	v_rcp_f32_e32 v17, v17
	s_nop 0
	v_mul_f32_e32 v16, v30, v16
	v_mul_f32_e32 v17, v31, v17
	s_nop 0
	v_mul_f32_e32 v26, v26, v16
	v_mul_f32_e32 v27, v27, v17
	v_mul_f32_e32 v16, 0xbfb8aa3b, v23
	v_exp_f32_e32 v16, v16
	s_nop 0
	v_add_f32_e32 v16, 1.0, v16
	v_rcp_f32_e32 v29, v16
	s_nop 0
	v_mul_f32_e32 v16, v22, v28
	v_mul_f32_e32 v17, v23, v29
	s_nop 0
	v_mul_f32_e32 v22, v18, v16
	v_mul_f32_e32 v23, v19, v17
	v_lshl_add_u64 v[28:29], v[32:33], 0, v[112:113]
	v_cvt_pk_bf16_f32 v16, v24, v25
	v_cvt_pk_bf16_f32 v17, v26, v27
	v_cvt_pk_bf16_f32 v18, v20, v21
	v_cvt_pk_bf16_f32 v19, v22, v23
	global_store_dwordx4 v[28:29], v[16:19], off
	s_nop 1
	v_mul_f32_e32 v19, 0xbfb8aa3b, v4
	v_exp_f32_e32 v19, v19
	v_mul_f32_e32 v18, 0xbfb8aa3b, v12
	v_exp_f32_e32 v18, v18
	v_add_u32_e32 v16, 0xb0, v144
	v_add_f32_e32 v19, 1.0, v19
	v_rcp_f32_e32 v20, v19
	v_mul_f32_e32 v19, 0xbfb8aa3b, v13
	v_exp_f32_e32 v19, v19
	v_add_f32_e32 v18, 1.0, v18
	v_rcp_f32_e32 v18, v18
	v_mad_i64_i32 v[16:17], s[22:23], v16, s66, v[138:139]
	v_add_f32_e32 v19, 1.0, v19
	v_rcp_f32_e32 v19, v19
	s_mov_b64 s[22:23], -1
	v_mul_f32_e32 v12, v12, v18
	v_mul_f32_e32 v13, v13, v19
	s_nop 0
	v_mul_f32_e32 v8, v8, v12
	v_mul_f32_e32 v9, v9, v13
	v_mul_f32_e32 v12, 0xbfb8aa3b, v5
	v_exp_f32_e32 v12, v12
	s_nop 0
	v_add_f32_e32 v12, 1.0, v12
	v_rcp_f32_e32 v21, v12
	s_nop 0
	v_mul_f32_e32 v4, v4, v20
	v_mul_f32_e32 v5, v5, v21
	s_nop 0
	v_mul_f32_e32 v4, v0, v4
	v_mul_f32_e32 v5, v1, v5
	v_mul_f32_e32 v1, 0xbfb8aa3b, v6
	v_exp_f32_e32 v1, v1
	v_mul_f32_e32 v0, 0xbfb8aa3b, v14
	v_exp_f32_e32 v0, v0
	v_add_f32_e32 v1, 1.0, v1
	v_rcp_f32_e32 v12, v1
	v_mul_f32_e32 v1, 0xbfb8aa3b, v15
	v_exp_f32_e32 v1, v1
	v_add_f32_e32 v0, 1.0, v0
	v_rcp_f32_e32 v0, v0
	v_add_f32_e32 v1, 1.0, v1
	v_rcp_f32_e32 v1, v1
	s_nop 0
	v_mul_f32_e32 v0, v14, v0
	v_mul_f32_e32 v1, v15, v1
	s_nop 0
	v_mul_f32_e32 v10, v10, v0
	v_mul_f32_e32 v11, v11, v1
	v_mul_f32_e32 v0, 0xbfb8aa3b, v7
	v_exp_f32_e32 v0, v0
	s_nop 0
	v_add_f32_e32 v0, 1.0, v0
	v_rcp_f32_e32 v13, v0
	s_nop 0
	v_mul_f32_e32 v0, v6, v12
	v_mul_f32_e32 v1, v7, v13
	s_nop 0
	v_mul_f32_e32 v6, v2, v0
	v_mul_f32_e32 v7, v3, v1
	v_lshl_add_u64 v[12:13], v[16:17], 0, v[112:113]
	v_cvt_pk_bf16_f32 v0, v8, v9
	v_cvt_pk_bf16_f32 v1, v10, v11
	v_cvt_pk_bf16_f32 v2, v4, v5
	v_cvt_pk_bf16_f32 v3, v6, v7
	global_store_dwordx4 v[12:13], v[0:3], off
	s_cbranch_vccnz .LBB0_1990
	s_andn2_b64 vcc, exec, s[8:9]
	s_cbranch_vccnz .LBB0_1989
	s_barrier
	s_branch .LBB0_1989
